# as the full-line nt set, plus nt on the last-issued Q fragment load of each query block (line's final use)
# baseline (speedup 1.0000x reference)
.LBB0_536:
	s_lshl_b32 s68, s25, 6
	s_cmp_lt_i32 s73, 1
	v_and_b32_e32 v188, 31, v186
	s_cbranch_scc1 .LBB0_549
	s_and_b64 s[42:43], s[8:9], exec
	s_cselect_b32 s37, s64, 0x9700000
	v_add_u32_e32 v2, s24, v188
	s_waitcnt lgkmcnt(0)
	s_add_u32 s42, s26, s37
	v_ashrrev_i32_e32 v19, 5, v186
	s_addc_u32 s43, s27, 0
	v_lshlrev_b64 v[4:5], 10, v[2:3]
	v_lshl_add_u64 v[4:5], s[42:43], 0, v[4:5]
	s_lshl_b32 s42, s68, 1
	s_mov_b32 s43, s36
	v_lshlrev_b32_e32 v6, 3, v19
	v_lshl_add_u64 v[4:5], v[4:5], 0, s[42:43]
	v_ashrrev_i32_e32 v7, 31, v6
	s_and_b64 s[42:43], s[14:15], exec
	v_lshl_add_u64 v[20:21], v[6:7], 1, v[4:5]
	s_cselect_b32 s42, 0, 0x8000
	s_mov_b32 s43, s36
	v_lshl_add_u64 v[22:23], v[20:21], 0, s[42:43]
	global_load_dwordx4 v[4:7], v[22:23], off offset:96
	global_load_dwordx4 v[8:11], v[22:23], off offset:64
	global_load_dwordx4 v[12:15], v[20:21], off offset:96
	global_load_dwordx4 v[132:135], v[20:21], off offset:64
	global_load_dwordx4 v[136:139], v[22:23], off offset:32
	global_load_dwordx4 v[140:143], v[22:23], off nt
	global_load_dwordx4 v[144:147], v[20:21], off offset:32
	global_load_dwordx4 v[148:151], v[20:21], off nt
	s_andn2_b64 vcc, exec, s[40:41]
	s_mov_b64 s[40:41], -1
	s_cbranch_vccnz .LBB0_539
	s_waitcnt vmcnt(0)
	s_mov_b64 s[40:41], 0
